# k19: k17 + barrier between chunk-state GEMM and carry chain removed; sample GLU kept in the merged phase behind an acquire on a per-block release counter (runs after the attention queue)
# baseline (speedup 1.0000x reference)
; #define GRID_BAR() xcd_barrier(xbar)
; __device__ __forceinline__ void xcd_barrier(const XcdBarrier& b) {
;     asm volatile("s_waitcnt vmcnt(0)" ::: "memory");
;     __syncthreads();
;     if (threadIdx.x == 0) {
; __global__ void __launch_bounds__(NTHR, 2) hymba_fwd(Params P) {
;     ...
;     }
;     }
;     GRID_BAR();
.LBB0_633:
	s_waitcnt vmcnt(0)
	s_barrier
	v_readfirstlane_b32 s8, v208
	s_nop 1
	s_cmp_gt_u32 s8, 63
	s_cbranch_scc1 .Lmy_rel_skip
	buffer_wbl2 sc1
	s_waitcnt vmcnt(0) lgkmcnt(0)
	s_mov_b64 s[8:9], exec
	s_mov_b64 exec, 1
	v_mov_b32_e32 v0, 0x300
	v_mov_b32_e32 v1, 1
	global_atomic_add v0, v1, s[92:93]
	s_mov_b64 exec, s[8:9]
.Lmy_rel_skip:
	s_mov_b64 s[6:7], exec
	v_readlane_b32 s8, v255, 4
	v_readlane_b32 s9, v255, 5
	v_readlane_b32 s70, v255, 8
	s_and_b64 s[8:9], s[6:7], s[8:9]
	v_readlane_b32 s71, v255, 9

; #define LAS __attribute__((address_space(3)))
; #define GRID_BAR() xcd_barrier(xbar)
; __global__ void __launch_bounds__(NTHR, 2) hymba_fwd(Params P) {
;     ...
;     GRID_BAR();
;     for (int it = blk; it < 128; it += G) {
;         const int mb = it & 15, ns = it >> 4;
;         LAS float* Cs = (LAS float*)lds; constexpr int ldc = 68;
;         __syncthreads();
;         skinny32(Cs, YSS + (size_t)(32 * mb) * SW, SW, WGLU, SW, 64, SW, [&](int ct) { return 64 * ns + 16 * ct; });
.LBB0_884:
	s_or_b64 exec, exec, s[4:5]
	v_writelane_b32 v255, s38, 44
	v_writelane_b32 v255, s39, 45
	s_waitcnt lgkmcnt(0)
	s_barrier
	s_cmpk_gt_i32 s2, 0x7f
	s_cbranch_scc1 .Lmy_glu_skip
	s_mov_b32 s5, 0
.Lmy_glu_spin:
	v_mov_b32_e32 v0, 0x300
	global_load_dword v1, v0, s[92:93] sc1
	s_waitcnt vmcnt(0)
	v_readfirstlane_b32 s4, v1
	s_add_u32 s5, s5, 1
	s_cmpk_gt_u32 s4, 0xff
	s_cbranch_scc1 .Lmy_glu_go
	s_cmp_gt_u32 s5, 0x100000
	s_cbranch_scc1 .Lmy_glu_go
	s_sleep 2
	s_branch .Lmy_glu_spin
.Lmy_glu_go:
	buffer_inv sc1
	s_add_u32 s4, s92, 0x2f500000
	s_addc_u32 s5, s93, 0
	v_mov_b32_e32 v161, 0
	s_mov_b64 s[6:7], 0x4080
	s_mov_b64 s[8:9], 0x40c0
	s_mov_b64 s[10:11], 0x4100
	s_mov_b64 s[12:13], 0x4140
	s_mov_b64 s[28:29], 0x4180
	s_mov_b64 s[34:35], 0x41c0
	s_movk_i32 s17, 0x100
	s_mov_b64 s[44:45], 0x80
	s_mov_b64 s[46:47], 0xc0
	s_mov_b64 s[48:49], 0x140
	s_mov_b64 s[58:59], 0x180
	s_mov_b64 s[60:61], 0x1c0
	s_brev_b32 s20, 63
	s_mov_b32 s21, s2
	s_branch .LBB0_688

; #define PG8_STAGE(bufoff, gbase, voff) do { _Pragma("unroll") for (int _i = 0; _i < 2; ++_i) \
;         __builtin_amdgcn_global_load_lds((const unsigned*)((const char*)(gbase) + (voff)[_i]), (LAS unsigned*)(lds + (bufoff) + ldsw + _i * 8192), 16, 0, 0); } while (0)
; #define PG8_WAIT_V(n) asm volatile("s_waitcnt vmcnt(" #n ")" ::: "memory")
; #define PG8_BAR __builtin_amdgcn_s_barrier()
;     __device__ bool next(int i, Unit& u) const {
;         const int L = i * G + c; if (L >= NG * (NCH / BM)) return false;
;         u.g = L / (NCH / BM); u.pm = L % (NCH / BM); u.pn = 0;
;         u.a = A + ((size_t)u.g * UXROWS + (size_t)u.pm * BM) * (UXR * 32); u.b = B + (size_t)u.g * wbytes; return true;
;     }
; template <class Epi, class Sched>
; __device__ __forceinline__ void gemm_phase(LAS unsigned char* lds, const Gemm g, const Sched& S, const Epi& E) {
;     ...
;     for (int i = 0; i < 2; ++i) { int R, C; stage_rc(tid * 16 + i * 8192, R, C); const int Rb = Epi::PERM ? ((R & ~31) + perm32(R & 31)) : R;
;         voffA[i] = (unsigned)R * g.lda + (g.aplane ? (unsigned)(C >> 4) * g.aplane + (unsigned)((C & 15) * 2) : (unsigned)(C * 2)); voffB[i] = (unsigned)Rb * g.ldb + (unsigned)(C * 2); }
;     const size_t kstepA = g.kstepA, kstepB = g.kstepB;
;     const size_t hstepA = (size_t)HALF * g.lda, hstepB = (size_t)HALF * g.ldb;
;     const unsigned ldsw = (unsigned)wid * 1024u;
;     const int aoff = lds_byte(wr * 64 + fr, fq * 8), boff = lds_byte(wc * 32 + fr, fq * 8);
;     ...
;     Unit cur, nxt; int ui = 0;
;     if (!S.next(0, cur)) return;
;     f32x4 acc[2][2][4][2];
; #pragma unroll
;     for (int a = 0; a < 2; ++a)
; #pragma unroll
;         for (int b = 0; b < 2; ++b)
; #pragma unroll
;             for (int m = 0; m < 4; ++m)
; #pragma unroll
;                 for (int n = 0; n < 2; ++n) acc[a][b][m][n] = (f32x4){0.f, 0.f, 0.f, 0.f};
;     bf16x8 At[4][2], B0[2][2], B1[2][2];
;     const char* cA = cur.a; const char* cB = cur.b;
;     PG8_WAIT_V(0);
;     PG8_STAGE(PG8_SB(0, 0), cB, voffB); PG8_STAGE(PG8_SB(0, 1), cB + hstepB, voffB); PG8_STAGE(PG8_SA(0, 0), cA, voffA); PG8_STAGE(PG8_SA(0, 1), cA + hstepA, voffA);
;     if (wr == 1) PG8_BAR;
;     PG8_WAIT_V(2); PG8_BAR;
;     PG8_STAGE(PG8_SB(1, 0), cB + kstepB, voffB); PG8_STAGE(PG8_SA(1, 0), cA + kstepA, voffA); PG8_STAGE(PG8_SB(1, 1), cB + hstepB + kstepB, voffB);
;     PG8_WAIT_V(6); PG8_BAR;
.Lmy_glu_end:
.Lmy_glu_skip:
.LBB0_894:
	s_and_b32 s16, s2, 31
	s_lshr_b32 s88, s2, 5
	s_lshl_b32 s88, s88, 1
	s_mul_i32 s0, s16, 0x306000
	s_mul_i32 s1, s88, 0x30000
	s_add_u32 s30, s22, s0
	s_addc_u32 s31, s23, 0
	s_add_u32 s30, s30, s1
	s_addc_u32 s31, s31, 0
	v_readlane_b32 s0, v255, 20
	s_add_u32 s4, s92, 0x2b400000
	v_mov_b32_e32 v8, v208
	v_readlane_b32 s1, v255, 21
	v_readlane_b32 s66, v255, 24
	s_addc_u32 s5, s93, 0
	s_and_b64 vcc, exec, s[0:1]
	v_readfirstlane_b32 s10, v8
	v_readlane_b32 s64, v255, 23
	v_readlane_b32 s67, v255, 25
	s_cbranch_vccz .LBB0_908
	v_lshlrev_b32_e32 v1, 4, v8
	v_add_u32_e32 v0, 0x2000, v1
	v_ashrrev_i32_e32 v2, 31, v0
	v_lshrrev_b32_e32 v2, 22, v2
	v_add_u32_e32 v2, v0, v2
	v_ashrrev_i32_e32 v2, 10, v2
	v_mul_i32_i24_e32 v3, 0x400, v2
	v_sub_u32_e32 v0, v0, v3
	v_lshrrev_b32_e32 v3, 4, v0
	v_bitop3_b32 v0, v3, v0, 32 bitop3:0x6c
	v_ashrrev_i32_e32 v3, 31, v0
	v_lshrrev_b32_e32 v3, 26, v3
	v_add_u32_e32 v3, v0, v3
	v_lshlrev_b32_e32 v5, 3, v2
	v_ashrrev_i32_e32 v4, 6, v3
	v_and_b32_e32 v5, -16, v5
	v_and_b32_e32 v3, 0xc0, v3
	v_add_u32_e32 v5, v4, v5
	v_sub_u32_e32 v0, v0, v3
	v_mov_b32_e32 v3, 1
	v_and_b32_e32 v4, 3, v4
	s_mov_b32 s13, 0xffffe0
	v_lshrrev_b32_e32 v6, 2, v5
	v_lshlrev_b32_e32 v7, 1, v5
	v_lshlrev_b32_e32 v2, 5, v2
	v_ashrrev_i16_sdwa v0, v3, sext(v0) dst_sel:DWORD dst_unused:UNUSED_PAD src0_sel:DWORD src1_sel:BYTE_0
	v_and_or_b32 v4, v5, s13, v4
	v_and_b32_e32 v6, 4, v6
	v_and_b32_e32 v7, 24, v7
	v_and_b32_e32 v2, 32, v2
	v_bfe_i32 v0, v0, 0, 16
	v_or3_b32 v4, v4, v6, v7
	v_add_lshl_u32 v0, v2, v0, 1
	s_movk_i32 s20, 0x300
	v_mad_u32_u24 v128, v4, s20, v0
	v_mad_u64_u32 v[130:131], s[8:9], v5, s20, v[0:1]
	v_bfe_i32 v0, v8, 27, 1
	v_lshrrev_b32_e32 v0, 22, v0
	v_add_u32_e32 v0, v1, v0
	v_and_b32_e32 v0, 0xfffffc00, v0
	v_sub_u32_e32 v0, v1, v0
	v_lshrrev_b32_e32 v1, 4, v0
	v_ashrrev_i32_e32 v4, 31, v8
	v_bitop3_b32 v0, v1, v0, 32 bitop3:0x6c
	v_lshrrev_b32_e32 v4, 26, v4
	v_ashrrev_i32_e32 v1, 31, v0
	v_add_u32_e32 v4, v8, v4
	s_mul_i32 s1, s16, 0x30000
	v_readlane_b32 s14, v255, 12
	v_lshrrev_b32_e32 v1, 26, v1
	v_ashrrev_i32_e32 v4, 6, v4
	s_mul_hi_i32 s0, s16, 0x30000
	s_add_u32 s42, s14, s1
	v_readlane_b32 s15, v255, 13
	v_add_u32_e32 v1, v0, v1
	v_lshlrev_b32_e32 v5, 3, v4
	s_addc_u32 s43, s15, s0
	s_ashr_i32 s12, s10, 6
	v_ashrrev_i32_e32 v2, 6, v1
	v_and_b32_e32 v5, -16, v5
	v_and_b32_e32 v1, 0xc0, v1
	s_ashr_i32 s11, s10, 8
	s_lshl_b32 s17, s12, 10
	v_add_u32_e32 v5, v2, v5
	v_sub_u32_e32 v0, v0, v1
	s_add_u32 s0, s30, 0x18000
	v_and_b32_e32 v2, 3, v2
	v_lshrrev_b32_e32 v6, 2, v5
	v_lshlrev_b32_e32 v7, 1, v5
	v_lshlrev_b32_e32 v4, 5, v4
	v_ashrrev_i16_sdwa v0, v3, sext(v0) dst_sel:DWORD dst_unused:UNUSED_PAD src0_sel:DWORD src1_sel:BYTE_0
	s_addc_u32 s1, s31, 0
	v_and_or_b32 v2, v5, s13, v2
	v_and_b32_e32 v6, 4, v6
	v_and_b32_e32 v7, 24, v7
	v_and_b32_e32 v4, 32, v4
	v_bfe_i32 v0, v0, 0, 16
	s_add_u32 s6, s42, 0x18000
	v_or3_b32 v2, v2, v6, v7
	v_add_lshl_u32 v0, v4, v0, 1
	s_addc_u32 s7, s43, 0
	v_mad_u32_u24 v132, v2, s20, v0
	v_mad_u64_u32 v[134:135], s[8:9], v5, s20, v[0:1]
	s_add_i32 s20, s17, 0
	s_waitcnt vmcnt(0)
	s_add_i32 m0, s20, 0x10000
	s_add_i32 s21, s20, 0x2000
	global_load_lds_dwordx4 v132, s[42:43]
	s_add_i32 m0, s20, 0x12000
	s_add_i32 s44, s20, 0x4000
	global_load_lds_dwordx4 v128, s[42:43]
	s_add_i32 m0, s20, 0x14000
	s_add_i32 s45, s20, 0x6000
	global_load_lds_dwordx4 v132, s[6:7]
	s_add_i32 m0, s20, 0x16000
	v_mov_b32_e32 v137, 0
	global_load_lds_dwordx4 v128, s[6:7]
	s_mov_b32 m0, s20
	v_mov_b32_e32 v133, v137
	global_load_lds_dwordx4 v134, s[30:31]
	s_mov_b32 m0, s21
	v_mov_b32_e32 v129, v137
	global_load_lds_dwordx4 v130, s[30:31]
	s_mov_b32 m0, s44
	v_mov_b32_e32 v135, v137
	global_load_lds_dwordx4 v134, s[0:1]
	s_mov_b32 m0, s45
	v_mov_b32_e32 v131, v137
	global_load_lds_dwordx4 v130, s[0:1]
	s_cmp_eq_u32 s11, 1
	v_lshl_add_u64 v[6:7], s[42:43], 0, v[132:133]
	v_lshl_add_u64 v[4:5], s[42:43], 0, v[128:129]
	v_lshl_add_u64 v[0:1], s[30:31], 0, v[134:135]
	s_cselect_b64 s[6:7], -1, 0
	s_cmp_lg_u32 s11, 1
	v_lshl_add_u64 v[2:3], s[30:31], 0, v[130:131]
	s_cbranch_scc1 .LBB0_897
	s_barrier
